# defer 1504 weight-conversion items from prologue into idle last-round CUs of gate/up phases
# speedup vs baseline: 1.0226x; 1.0226x over previous
; #define LAS __attribute__((address_space(3)))
; #define LANE_ID() ({ int l_ = (int)__builtin_amdgcn_mbcnt_hi(~0u, __builtin_amdgcn_mbcnt_lo(~0u, 0u)); asm volatile("" : "+v"(l_)); l_; })
; #define WS_BASE() unsigned char* ws = args.ws; int bidp = bid, Gp = G, wavep = wave; asm volatile("" : "+s"(ws), "+s"(bidp), "+s"(Gp), "+s"(wavep));
; __global__ void __launch_bounds__(NTHREADS, 2) mega_fwd(Args args) {
;     extern __shared__ __attribute__((aligned(16))) unsigned char lds_raw[];
;     cg::grid_group grid = cg::this_grid();
;     LAS unsigned char* lds = (LAS unsigned char*)lds_raw;
;     const int wave = __builtin_amdgcn_readfirstlane(threadIdx.x >> 6);
;     const int G = gridDim.x, bid = blockIdx.x;
;     ...
;     {
;         WS_BASE();
;         const int lane = LANE_ID(), tid = wave * 64 + lane, gt = bid * NTHREADS + tid, ngt = G * NTHREADS, gw = bid * NWAVES + wave, ngw = G * NWAVES;
;         float* ssq_x = P_SSQX; float* cosT = P_COS; float* sinT = P_SIN; bf16* XB = P_XB; const float* x_in = args.in[0];
;         if (bid == 0) for (int i = tid; i < 8192; i += NTHREADS) ((unsigned*)(ws + WS_BAR))[i] = 0u;
_Z8mega_fwd4Args:
	s_load_dwordx4 s[8:11], s[0:1], 0x88
	v_and_b32_e32 v1, 0x3ff, v0
	s_mov_b32 s72, s2
	s_mov_b32 s98, 0
	s_add_u32 s2, s0, 0x90
	v_readfirstlane_b32 s33, v1
	s_addc_u32 s3, s1, 0
	s_lshr_b32 s73, s33, 6
	s_mov_b32 s4, s72
	s_mov_b32 s5, s73
	s_waitcnt lgkmcnt(0)
	s_mov_b64 s[12:13], s[8:9]
	v_writelane_b32 v254, s8, 0
	s_mov_b32 s6, s10
	v_mbcnt_lo_u32_b32 v2, -1, 0
	v_mbcnt_hi_u32_b32 v211, -1, v2
	v_mov_b32_e32 v2, v211
	s_and_b32 s4, s33, 0xffffffc0
	v_writelane_b32 v254, s9, 1
	s_cmp_eq_u32 s72, 0
	v_add_u32_e32 v4, s4, v2
	s_movk_i32 s6, 0x2000
	v_writelane_b32 v254, s10, 2
	s_cselect_b64 s[4:5], -1, 0
	v_cmp_gt_i32_e32 vcc, s6, v4
	v_writelane_b32 v254, s11, 3
	s_and_b64 s[6:7], s[4:5], vcc
	s_and_saveexec_b64 s[4:5], s[6:7]
	s_cbranch_execz .LBB0_8
	v_max_i32_e32 v3, 0x1e00, v4
	v_sub_u32_e32 v3, v3, v4
	s_movk_i32 s6, 0x1ff
	v_add_u32_e32 v3, 0x1ff, v3
	v_cmp_lt_u32_e32 vcc, s6, v3
	s_mov_b64 s[8:9], -1
	v_mov_b32_e32 v6, v4
	s_and_saveexec_b64 s[6:7], vcc
	s_cbranch_execz .LBB0_5
	v_lshrrev_b32_e32 v3, 9, v3
	v_add_u32_e32 v3, 1, v3
	s_add_u32 s8, s12, 0x80000
	v_and_b32_e32 v8, 0xfffffe, v3
	v_add_u32_e32 v5, 0x200, v4
	s_addc_u32 s9, s13, 0
	s_mov_b64 s[10:11], 0
	v_mov_b32_e32 v9, 0
	v_mov_b32_e32 v10, v8
	v_mov_b64_e32 v[6:7], v[4:5]

; __device__ __forceinline__ unsigned cvt_pk_bf16(float lo, float hi) { unsigned r; asm volatile("v_cvt_pk_bf16_f32 %0, %1, %2" : "=v"(r) : "v"(lo), "v"(hi)); return r; }
; #define LAS __attribute__((address_space(3)))
; __device__ __forceinline__ void tr_item_cu(const float* __restrict__ W, int K, int N, bf16* __restrict__ WT, const float* rowgain, int mode, LAS unsigned char* buf, int item, int wave, int lane) {
;     const int nblk = N >> 7, kb = item / nblk, nb = item - kb * nblk, k0 = 256 * kb, n0 = 128 * nb;
;     const int hr = lane >> 5, c = lane & 31, kw = 32 * wave + 16 * hr;
;     f32x4 v[16];
;     const float* src = W + (size_t)(k0 + kw) * N + n0 + 4 * c;
; #pragma unroll
;     for (int j = 0; j < 16; ++j) v[j] = __builtin_nontemporal_load((const f32x4*)(src + (size_t)j * N));
;     if (rowgain) {
; #pragma unroll
;         for (int q = 0; q < 4; ++q) { const f32x4 r4 = *(const f32x4*)(rowgain + k0 + kw + 4 * q);
; #pragma unroll
;             for (int e = 0; e < 4; ++e) v[4 * q + e] = v[4 * q + e] * r4[e]; }
;     }
; #pragma unroll
;     for (int i = 0; i < 4; ++i) {
;         u32x4 lo, hi;
;         lo.x = pg8::cvt_pk_bf16(v[0][i], v[1][i]);   lo.y = pg8::cvt_pk_bf16(v[2][i], v[3][i]);   lo.z = pg8::cvt_pk_bf16(v[4][i], v[5][i]);   lo.w = pg8::cvt_pk_bf16(v[6][i], v[7][i]);
;         hi.x = pg8::cvt_pk_bf16(v[8][i], v[9][i]);   hi.y = pg8::cvt_pk_bf16(v[10][i], v[11][i]); hi.z = pg8::cvt_pk_bf16(v[12][i], v[13][i]); hi.w = pg8::cvt_pk_bf16(v[14][i], v[15][i]);
;         LAS unsigned char* p = buf + (4 * c + i) * TCP + kw * 2;
;         *(LAS u32x4*)p = lo; *(LAS u32x4*)(p + 16) = hi;
;     }
;     __syncthreads();
; #pragma unroll
;     for (int m = 0; m < 8; ++m) { const int row = 16 * wave + 2 * m + hr;
;         const u32x4 o = *(const LAS u32x4*)(buf + row * TCP + c * 16);
;         asm volatile("global_store_dwordx4 %0, %1, off sc1\n\ts_nop 1" :: "v"(WT + (size_t)row_map(mode, n0 + row) * K + k0 + 8 * c), "v"(o) : "memory"); }
; __global__ void __launch_bounds__(NTHREADS, 2) mega_fwd(Args args) {
;     ...
;         int nbuf = 0;
;         for (int it = bid; it < DEPTH * I_LAYER; it += G, nbuf ^= 1) {
;             const int itr = DEPTH * I_LAYER - 1 - it;
;             const int l = itr / I_LAYER; int r = itr - l * I_LAYER;
.Ldc_pre:
	v_ashrrev_i32_e32 v3, 5, v2
	v_lshl_add_u32 v77, s73, 4, v3
	v_add_u32_e32 v82, 2, v77
	v_lshrrev_b32_e32 v6, 2, v82
	v_and_b32_e32 v84, 16, v6
	v_lshlrev_b32_e32 v6, 2, v82
	v_and_b32_e32 v6, 16, v6
	v_lshrrev_b32_e32 v7, 1, v82
	v_add_u32_e32 v86, 4, v77
	v_and_or_b32 v85, v7, 12, v6
	v_lshrrev_b32_e32 v6, 2, v86
	v_and_b32_e32 v88, 16, v6
	v_lshlrev_b32_e32 v6, 2, v86
	v_and_b32_e32 v6, 16, v6
	v_lshrrev_b32_e32 v7, 1, v86
	v_add_u32_e32 v90, 6, v77
	v_and_or_b32 v89, v7, 12, v6
	v_lshrrev_b32_e32 v6, 2, v90
	v_and_b32_e32 v92, 16, v6
	v_lshlrev_b32_e32 v6, 2, v90
	v_and_b32_e32 v6, 16, v6
	v_lshrrev_b32_e32 v7, 1, v90
	v_add_u32_e32 v97, 10, v77
	v_and_or_b32 v93, v7, 12, v6
	v_lshrrev_b32_e32 v7, 2, v97
	s_add_u32 s36, s12, 0x900000
	v_and_b32_e32 v99, 16, v7
	v_lshlrev_b32_e32 v7, 2, v97
	s_addc_u32 s37, s13, 0
	s_load_dwordx2 s[12:13], s[0:1], 0x8
	s_load_dwordx4 s[4:7], s[0:1], 0x20
	s_load_dwordx4 s[8:11], s[0:1], 0x58
	s_load_dwordx2 s[14:15], s[0:1], 0x30
	s_load_dwordx2 s[16:17], s[0:1], 0x78
	v_and_b32_e32 v7, 16, v7
	v_lshrrev_b32_e32 v8, 1, v97
	v_add_u32_e32 v101, 12, v77
	v_and_or_b32 v100, v8, 12, v7
	v_lshrrev_b32_e32 v7, 2, v101
	v_and_b32_e32 v103, 16, v7
	v_lshlrev_b32_e32 v7, 2, v101
	v_and_b32_e32 v7, 16, v7
	v_lshrrev_b32_e32 v8, 1, v101
	v_add_u32_e32 v105, 14, v77
	s_lshl_b32 s18, s73, 5
	v_add_u32_e32 v94, 8, v77
	v_and_or_b32 v104, v8, 12, v7
	v_lshrrev_b32_e32 v7, 2, v105
	v_and_b32_e32 v4, 31, v2
	v_lshl_add_u32 v66, v3, 4, s18
	v_lshrrev_b32_e32 v5, 2, v77
	v_lshlrev_b32_e32 v3, 2, v3
	v_lshrrev_b32_e32 v6, 2, v94
	v_and_b32_e32 v107, 16, v7
	v_lshlrev_b32_e32 v7, 2, v105
	v_lshlrev_b32_e32 v2, 2, v4
	v_mov_b32_e32 v69, 0
	v_mul_u32_u24_e32 v76, 0x840, v4
	v_lshlrev_b32_e32 v78, 4, v4
	v_lshlrev_b32_e32 v4, 3, v4
	s_movk_i32 s18, 0x210
	v_and_b32_e32 v80, 0x7f, v77
	v_and_b32_e32 v81, 16, v5
	v_and_b32_e32 v3, 16, v3
	v_lshrrev_b32_e32 v5, 1, v77
	v_and_b32_e32 v83, 0x7f, v82
	v_and_b32_e32 v87, 0x7f, v86
	v_and_b32_e32 v91, 0x7f, v90
	v_and_b32_e32 v95, 0x7f, v94
	v_and_b32_e32 v96, 16, v6
	v_lshrrev_b32_e32 v6, 1, v94
	v_and_b32_e32 v98, 0x7f, v97
	v_and_b32_e32 v102, 0x7f, v101
	v_and_b32_e32 v106, 0x7f, v105
	v_and_b32_e32 v7, 16, v7
	v_lshrrev_b32_e32 v8, 1, v105
	v_ashrrev_i32_e32 v67, 31, v66
	v_lshlrev_b32_e32 v75, 1, v66
	v_mul_lo_u32 v79, v77, s18
	v_and_or_b32 v108, v8, 12, v7
	v_or_b32_e32 v109, 0x80, v80
	v_or_b32_e32 v110, 0x80, v83
	v_or_b32_e32 v111, 0x80, v87
	v_or_b32_e32 v112, 0x80, v91
	v_or_b32_e32 v113, 0x80, v95
	v_or_b32_e32 v114, 0x80, v98
	v_or_b32_e32 v115, 0x80, v102
	v_or_b32_e32 v116, 0x80, v106
	v_and_or_b32 v117, v5, 12, v3
	v_and_or_b32 v118, v6, 12, v3
	s_mov_b32 s19, 0
	s_sub_i32 s38, 0, s72
	s_sub_i32 s39, 0x137f, s72
	v_lshlrev_b32_e32 v70, 2, v2
	v_mov_b32_e32 v71, v69
	s_movk_i32 s40, 0xff00
	s_movk_i32 s41, 0xf7ff
	s_movk_i32 s42, 0xffe3
	v_lshlrev_b32_e32 v68, 1, v4
	s_mov_b32 s43, 0
	s_mov_b32 s44, s72
	s_cmp_lg_u32 s98, 0
	s_cbranch_scc1 .Ldc_ovr
	v_readlane_b32 s100, v254, 2
	s_movk_i32 s101, 0x137f
	s_nop 1
	s_mov_b32 s99, s100
	s_cmpk_lg_i32 s100, 0x100
	s_cbranch_scc1 .LBB0_33
	s_cmpk_lt_i32 s72, 0x80
	s_cbranch_scc1 .Ldc_lowhalf
	s_addk_i32 s44, 0x5e0
	s_sub_i32 s38, 0, s44
	s_sub_i32 s39, 0x137f, s44
	s_branch .LBB0_33
.Ldc_lowhalf:
	s_movk_i32 s100, 0x6e0
	s_branch .LBB0_33
.Ldc_ovr:
	s_mov_b32 s44, s99
	s_sub_i32 s38, 0, s99
	s_sub_i32 s39, 0x137f, s99
	s_movk_i32 s99, 0x80
	s_branch .LBB0_33

; #define LAS __attribute__((address_space(3)))
; __device__ __forceinline__ void tr_item_cu(const float* __restrict__ W, int K, int N, bf16* __restrict__ WT, const float* rowgain, int mode, LAS unsigned char* buf, int item, int wave, int lane) {
;     ...
;     for (int m = 0; m < 8; ++m) { const int row = 16 * wave + 2 * m + hr;
;         const u32x4 o = *(const LAS u32x4*)(buf + row * TCP + c * 16);
;         asm volatile("global_store_dwordx4 %0, %1, off sc1\n\ts_nop 1" :: "v"(WT + (size_t)row_map(mode, n0 + row) * K + k0 + 8 * c), "v"(o) : "memory"); }
; __global__ void __launch_bounds__(NTHREADS, 2) mega_fwd(Args args) {
;     ...
;         for (int it = bid; it < DEPTH * I_LAYER; it += G, nbuf ^= 1) {
.LBB0_32:
	v_ashrrev_i32_e32 v8, 31, v9
	v_mul_lo_u32 v10, s21, v9
	v_mul_lo_u32 v11, s20, v8
	v_mad_u64_u32 v[8:9], s[20:21], s20, v9, 0
	s_load_dwordx4 s[20:23], s[0:1], 0x88
	v_add3_u32 v9, v9, v11, v10
	v_lshl_add_u64 v[6:7], v[8:9], 1, v[6:7]
	s_waitcnt lgkmcnt(0)
	global_store_dwordx4 v[6:7], v[2:5], off sc1
	s_nop 1
	s_xor_b32 s43, s43, 1
	s_add_i32 s44, s44, s100
	s_sub_i32 s38, s38, s100
	s_sub_i32 s39, s39, s100
	s_mov_b32 s100, s99
	s_cmp_gt_i32 s44, s101
	s_cbranch_scc1 .LBB0_184

; __device__ __forceinline__ bool xb_leader(int wave) { int l_ = (int)__builtin_amdgcn_mbcnt_hi(~0u, __builtin_amdgcn_mbcnt_lo(~0u, 0u)); asm volatile("" : "+v"(l_)); return wave == 0 && l_ == 0; }
; __global__ void __launch_bounds__(NTHREADS, 2) mega_fwd(Args args) {
;     ...
;         for (int it = bid; it < DEPTH * I_LAYER; it += G, nbuf ^= 1) {
;             const int itr = DEPTH * I_LAYER - 1 - it;
;             const int l = itr / I_LAYER; int r = itr - l * I_LAYER;
;             unsigned char* WL = P_WL(l);
;             const float* W; int K, N, mode = 0; bf16* WT; const float* rg = nullptr;
;             if (r < 3 * I_GU) { const int w = r / I_GU; r -= w * I_GU;
;                 if (w < 2) { W = args.in[2 + w] + (size_t)l * D * FF; K = D; N = FF; WT = (bf16*)(WL + OFF_WGU1); rg = args.in[1] + (size_t)l * D; mode = 1 + w; }
;                 else { W = args.in[4] + (size_t)l * FF * D; K = FF; N = D; WT = (bf16*)(WL + OFF_WD1); } }
;             else if ((r -= 3 * I_GU) < 3 * I_GU) { const int w = r / I_GU; r -= w * I_GU;
;                 if (w < 2) { W = args.in[13 + w] + (size_t)l * D * FF; K = D; N = FF; WT = (bf16*)(WL + OFF_WGU2); rg = args.in[12] + (size_t)l * D; mode = 1 + w; }
;                 else { W = args.in[15] + (size_t)l * FF * D; K = FF; N = D; WT = (bf16*)(WL + OFF_WD2); } }
;             else if ((r -= 3 * I_GU) < I_IN) { W = args.in[6] + (size_t)l * D * INW; K = D; N = INW; WT = (bf16*)(WL + OFF_WIN); rg = args.in[5] + (size_t)l * D; mode = 3; }
;             else { r -= I_IN; W = args.in[11] + (size_t)l * D * D; K = D; N = D; WT = (bf16*)(WL + OFF_WOUT); }
;             tr_item_cu(W, K, N, WT, rg, mode, lds + nbuf * TC_BUF, r, wave, lane);
;         }
;     ...
;         asm volatile("s_waitcnt vmcnt(0)" ::: "memory");
;         __syncthreads();
;         const bool ldr = xb_leader(wave);
;         if (ldr) { __builtin_amdgcn_fence(__ATOMIC_RELEASE, "agent"); asm volatile("s_waitcnt vmcnt(0)" ::: "memory"); }
.Ldc_enter:
	v_writelane_b32 v0, s2, 2
	v_writelane_b32 v0, s3, 3
	v_writelane_b32 v0, s4, 4
	v_writelane_b32 v0, s5, 5
	v_writelane_b32 v0, s6, 6
	v_writelane_b32 v0, s7, 7
	v_writelane_b32 v0, s8, 8
	v_writelane_b32 v0, s9, 9
	v_writelane_b32 v0, s10, 10
	v_writelane_b32 v0, s11, 11
	v_writelane_b32 v0, s12, 12
	v_writelane_b32 v0, s13, 13
	v_writelane_b32 v0, s14, 14
	v_writelane_b32 v0, s15, 15
	v_writelane_b32 v0, s16, 16
	v_writelane_b32 v0, s17, 17
	v_writelane_b32 v0, s18, 18
	v_writelane_b32 v0, s19, 19
	v_writelane_b32 v0, s20, 20
	v_writelane_b32 v0, s21, 21
	v_writelane_b32 v0, s22, 22
	v_writelane_b32 v0, s23, 23
	v_writelane_b32 v0, s24, 24
	v_writelane_b32 v0, s25, 25
	v_writelane_b32 v0, s26, 26
	v_writelane_b32 v0, s27, 27
	v_writelane_b32 v0, s28, 28
	v_writelane_b32 v0, s29, 29
	v_writelane_b32 v0, s30, 30
	v_writelane_b32 v0, s31, 31
	v_writelane_b32 v0, s32, 32
	v_writelane_b32 v0, s33, 33
	v_writelane_b32 v0, s34, 34
	v_writelane_b32 v0, s35, 35
	v_writelane_b32 v0, s36, 36
	v_writelane_b32 v0, s37, 37
	v_writelane_b32 v0, s38, 38
	v_writelane_b32 v0, s39, 39
	v_writelane_b32 v0, s40, 40
	v_writelane_b32 v0, s41, 41
	v_writelane_b32 v0, s42, 42
	v_writelane_b32 v0, s43, 43
	v_writelane_b32 v0, s44, 44
	v_writelane_b32 v0, s45, 45
	v_writelane_b32 v0, s46, 46
	v_writelane_b32 v0, s47, 47
	v_writelane_b32 v0, s48, 48
	v_lshlrev_b32_e32 v1, 2, v211
	s_lshl_b32 s4, s73, 11
	s_add_i32 s4, s4, 0x21000
	v_add_u32_e32 v1, s4, v1
	ds_write_b32 v1, v96 offset:0
	ds_write_b32 v1, v97 offset:256
	ds_write_b32 v1, v130 offset:512
	ds_write_b32 v1, v131 offset:768
	ds_write_b32 v1, v132 offset:1024
	ds_write_b32 v1, v133 offset:1280
	ds_write_b32 v1, v134 offset:1536
	ds_write_b32 v1, v135 offset:1792
	v_readlane_b32 s4, v255, 28
	v_readlane_b32 s0, v255, 62
	v_readlane_b32 s1, v255, 63
	v_readlane_b32 s12, v254, 0
	v_readlane_b32 s13, v254, 1
	v_mov_b32_e32 v2, v211
	s_cmp_lg_u32 s4, 0
	s_cselect_b32 s4, 2, 0
	s_add_i32 s4, s4, s98
	s_movk_i32 s99, 0x460
	s_movk_i32 s101, 0x65f
	s_cmp_eq_u32 s4, 2
	s_cselect_b32 s99, 0x2e0, s99
	s_cselect_b32 s101, 0x45f, s101
	s_cmp_eq_u32 s4, 3
	s_cselect_b32 s99, 0x80, s99
	s_cselect_b32 s101, 0x17f, s101
	s_cmp_eq_u32 s4, 4
	s_cselect_b32 s99, 0x180, s99
	s_cselect_b32 s101, 0x2df, s101
	s_sub_i32 s5, s72, 0x80
	s_add_i32 s99, s99, s5
	s_movk_i32 s100, 0x80
	s_waitcnt lgkmcnt(0)
	s_nop 4
	s_branch .Ldc_pre
.Ldc_return:
	s_waitcnt vmcnt(0) lgkmcnt(0)
	s_barrier
	ds_read_b32 v96, v1 offset:0
	ds_read_b32 v97, v1 offset:256
	ds_read_b32 v130, v1 offset:512
	ds_read_b32 v131, v1 offset:768
	ds_read_b32 v132, v1 offset:1024
	ds_read_b32 v133, v1 offset:1280
	ds_read_b32 v134, v1 offset:1536
	ds_read_b32 v135, v1 offset:1792
	s_waitcnt lgkmcnt(0)
	v_readlane_b32 s2, v0, 2
	v_readlane_b32 s3, v0, 3
	v_readlane_b32 s4, v0, 4
	v_readlane_b32 s5, v0, 5
	v_readlane_b32 s6, v0, 6
	v_readlane_b32 s7, v0, 7
	v_readlane_b32 s8, v0, 8
	v_readlane_b32 s9, v0, 9
	v_readlane_b32 s10, v0, 10
	v_readlane_b32 s11, v0, 11
	v_readlane_b32 s12, v0, 12
	v_readlane_b32 s13, v0, 13
	v_readlane_b32 s14, v0, 14
	v_readlane_b32 s15, v0, 15
	v_readlane_b32 s16, v0, 16
	v_readlane_b32 s17, v0, 17
	v_readlane_b32 s18, v0, 18
	v_readlane_b32 s19, v0, 19
	v_readlane_b32 s20, v0, 20
	v_readlane_b32 s21, v0, 21
	v_readlane_b32 s22, v0, 22
	v_readlane_b32 s23, v0, 23
	v_readlane_b32 s24, v0, 24
	v_readlane_b32 s25, v0, 25
	v_readlane_b32 s26, v0, 26
	v_readlane_b32 s27, v0, 27
	v_readlane_b32 s28, v0, 28
	v_readlane_b32 s29, v0, 29
	v_readlane_b32 s30, v0, 30
	v_readlane_b32 s31, v0, 31
	v_readlane_b32 s32, v0, 32
	v_readlane_b32 s33, v0, 33
	v_readlane_b32 s34, v0, 34
	v_readlane_b32 s35, v0, 35
	v_readlane_b32 s36, v0, 36
	v_readlane_b32 s37, v0, 37
	v_readlane_b32 s38, v0, 38
	v_readlane_b32 s39, v0, 39
	v_readlane_b32 s40, v0, 40
	v_readlane_b32 s41, v0, 41
	v_readlane_b32 s42, v0, 42
	v_readlane_b32 s43, v0, 43
	v_readlane_b32 s44, v0, 44
	v_readlane_b32 s45, v0, 45
	v_readlane_b32 s46, v0, 46
	v_readlane_b32 s47, v0, 47
	v_readlane_b32 s48, v0, 48
	s_nop 4
	s_cmp_eq_u32 s98, 1
	s_mov_b32 s98, 0
	s_cbranch_scc1 .Ldc_retA
	s_branch .Ldc_retB
.LBB0_184:
	s_cmp_lg_u32 s98, 0
	s_cbranch_scc1 .Ldc_return
	s_waitcnt vmcnt(0)
	v_mov_b32_e32 v2, v211
	s_cmp_lt_u32 s33, 64
	s_barrier
	s_cselect_b64 s[78:79], -1, 0
	v_cmp_eq_u32_e32 vcc, 0, v2
	s_and_b64 s[4:5], s[78:79], vcc
	s_and_saveexec_b64 s[6:7], s[4:5]
	s_cbranch_execz .LBB0_186
	buffer_wbl2 sc1
	s_waitcnt vmcnt(0)
	s_waitcnt vmcnt(0)

; #define LAS __attribute__((address_space(3)))
; #define WS_BASE() unsigned char* ws = args.ws; int bidp = bid, Gp = G, wavep = wave; asm volatile("" : "+s"(ws), "+s"(bidp), "+s"(Gp), "+s"(wavep));
; __global__ void __launch_bounds__(NTHREADS, 2) mega_fwd(Args args) {
;     ...
;     const XcdBarrier xbar = xcd_barrier_post((unsigned*)(args.ws + WS_BAR), (volatile LAS unsigned*)(lds + XB_ST_OFF), wave);
; #pragma unroll 1
;     for (int l = 0; l < DEPTH; ++l) {
;         { WS_BASE();
;           pg8::Gemm g{P_XB, (const bf16*)(P_WL(l) + OFF_WGU1), S, NGU, D}; pg8::StaticOrder so; so.init(S, NGU, Gp, bidp);
;           pg8::EpiSwiglu E{P_H, FF, P_SSQX + (size_t)(3 * l + 0) * S * 8};
;           pg8::gemm_phase<pg8::EpiSwiglu, pg8::StaticOrder, true, true, D, D, 0>(lds, g, so, E, wavep);
.LBB0_201:
	s_or_b64 exec, exec, s[4:5]
	s_load_dwordx4 s[12:15], s[0:1], 0x88
	s_load_dword s5, s[0:1], 0x98
	v_add_u32_e32 v0, 64, v74
	v_cmp_lt_i32_e32 vcc, v73, v0
	v_mov_b32_e32 v220, 0x358637bd
	s_waitcnt lgkmcnt(0)
	s_mul_i32 s4, s15, s14
	s_mul_i32 s36, s4, s5
	s_add_u32 s4, s12, 0x80200
	s_addc_u32 s5, s13, 0
	s_add_u32 s58, s12, 0x80400
	v_writelane_b32 v254, s4, 4
	s_addc_u32 s59, s13, 0
	v_cndmask_b32_e32 v1, v211, v73, vcc
	v_writelane_b32 v254, s5, 5
	s_add_u32 s4, s12, 0x80500
	s_addc_u32 s5, s13, 0
	v_writelane_b32 v254, s4, 6
	v_cmp_lt_i32_e32 vcc, v72, v0
	v_lshlrev_b32_e32 v218, 2, v1
	v_writelane_b32 v254, s5, 7
	s_add_u32 s4, s12, 0x80600
	s_addc_u32 s5, s13, 0
	v_writelane_b32 v254, s4, 8
	v_cndmask_b32_e32 v0, v211, v72, vcc
	v_lshlrev_b32_e32 v219, 2, v0
	v_writelane_b32 v254, s5, 9
	s_add_u32 s4, s12, 0x80700
	s_addc_u32 s5, s13, 0
	v_writelane_b32 v254, s4, 10
	s_movk_i32 s33, 0x2000
	v_mov_b32_e32 v97, 0
	v_writelane_b32 v254, s5, 11
	s_add_u32 s4, s12, 0x80800
	s_addc_u32 s5, s13, 0
	v_writelane_b32 v254, s4, 12
	s_mov_b32 s62, 0xffff0000
	s_movk_i32 s63, 0x2c00
	v_writelane_b32 v254, s5, 13
	s_add_u32 s4, s12, 0x80900
	s_addc_u32 s5, s13, 0
	v_writelane_b32 v254, s4, 14
	v_mov_b32_e32 v221, 1
	v_mov_b64_e32 v[194:195], 0x57f
	v_writelane_b32 v254, s5, 15
	s_add_u32 s4, s12, 0x80a00
	s_addc_u32 s5, s13, 0
	v_writelane_b32 v254, s4, 16
	v_mov_b64_e32 v[252:253], 0x580
	v_mov_b64_e32 v[200:201], 0xff
	v_writelane_b32 v254, s5, 17
	s_add_u32 s4, s12, 0x80b00
	s_addc_u32 s5, s13, 0
	v_writelane_b32 v254, s4, 18
	v_mov_b32_e32 v222, 0xff800000
	v_mov_b32_e32 v223, 0x42800000
	v_writelane_b32 v254, s5, 19
	s_add_u32 s4, s12, 0x80c00
	s_addc_u32 s5, s13, 0
	v_writelane_b32 v254, s4, 20
	v_not_b32_e32 v224, 63
	v_mov_b32_e32 v225, 0x1fff
	v_writelane_b32 v254, s5, 21
	s_add_u32 s4, s12, 0x80d00
	s_addc_u32 s5, s13, 0
	v_writelane_b32 v254, s4, 22
	s_mov_b64 s[34:35], 0
	s_mov_b64 s[22:23], 0x80
	v_writelane_b32 v254, s5, 23
	s_add_u32 s4, s12, 0x80e00
	s_addc_u32 s5, s13, 0
	v_writelane_b32 v254, s4, 24
	s_mov_b64 s[24:25], 0x100
	s_mov_b32 s56, s77
	v_writelane_b32 v254, s5, 25
	s_add_u32 s4, s12, 0x80f00
	s_addc_u32 s5, s13, 0
	v_writelane_b32 v254, s4, 26
	s_nop 1
	v_writelane_b32 v254, s5, 27
	s_add_u32 s4, s12, 0x81000
	s_addc_u32 s5, s13, 0
	v_writelane_b32 v254, s4, 28
	s_nop 1
	v_writelane_b32 v254, s5, 29
	s_add_u32 s4, s12, 0x81100
	s_addc_u32 s5, s13, 0
	v_writelane_b32 v254, s4, 30
	s_nop 1
	v_writelane_b32 v254, s5, 31
	s_add_u32 s4, s12, 0x81200
	s_addc_u32 s5, s13, 0
	v_writelane_b32 v254, s4, 32
	s_nop 1
	v_writelane_b32 v254, s5, 33
	s_add_u32 s4, s12, 0x81300
	s_addc_u32 s5, s13, 0
	v_writelane_b32 v254, s4, 34
	s_cmp_eq_u32 s8, 15
	s_nop 0
	v_writelane_b32 v254, s5, 35
	s_cselect_b64 s[4:5], -1, 0
	v_writelane_b32 v254, s4, 36
	s_cmp_eq_u32 s8, 14
	s_nop 0
	v_writelane_b32 v254, s5, 37
	s_cselect_b64 s[4:5], -1, 0
	v_writelane_b32 v254, s4, 38
	s_cmp_eq_u32 s8, 13
	s_nop 0
	v_writelane_b32 v254, s5, 39
	s_cselect_b64 s[4:5], -1, 0
	v_writelane_b32 v254, s4, 40
	s_cmp_eq_u32 s8, 12
	s_nop 0
	v_writelane_b32 v254, s5, 41
	s_cselect_b64 s[4:5], -1, 0
	v_writelane_b32 v254, s4, 42
	s_cmp_eq_u32 s8, 11
	s_nop 0
	v_writelane_b32 v254, s5, 43
	s_cselect_b64 s[4:5], -1, 0
	v_writelane_b32 v254, s4, 44
	s_cmp_eq_u32 s8, 10
	s_nop 0
	v_writelane_b32 v254, s5, 45
	s_cselect_b64 s[4:5], -1, 0
	v_writelane_b32 v254, s4, 46
	s_cmp_eq_u32 s8, 9
	s_nop 0
	v_writelane_b32 v254, s5, 47
	s_cselect_b64 s[4:5], -1, 0
	v_writelane_b32 v254, s4, 48
	s_cmp_eq_u32 s8, 8
	s_nop 0
	v_writelane_b32 v254, s5, 49
	s_cselect_b64 s[4:5], -1, 0
	v_writelane_b32 v254, s4, 50
	s_cmp_eq_u32 s8, 7
	s_nop 0
	v_writelane_b32 v254, s5, 51
	s_cselect_b64 s[4:5], -1, 0
	v_writelane_b32 v254, s4, 52
	s_cmp_eq_u32 s8, 6
	s_nop 0
	v_writelane_b32 v254, s5, 53
	s_cselect_b64 s[4:5], -1, 0
	v_writelane_b32 v254, s4, 54
	s_cmp_eq_u32 s8, 5
	s_nop 0
	v_writelane_b32 v254, s5, 55
	s_cselect_b64 s[4:5], -1, 0
	v_writelane_b32 v254, s4, 56
	s_cmp_eq_u32 s8, 4
	s_nop 0
	v_writelane_b32 v254, s5, 57
	s_cselect_b64 s[4:5], -1, 0
	v_writelane_b32 v254, s4, 58
	s_cmp_eq_u32 s8, 3
	s_nop 0
	v_writelane_b32 v254, s5, 59
	s_cselect_b64 s[4:5], -1, 0
	v_writelane_b32 v254, s4, 60
	s_cmp_eq_u32 s8, 2
	s_nop 0
	v_writelane_b32 v254, s5, 61
	s_cselect_b64 s[4:5], -1, 0
	v_writelane_b32 v254, s4, 62
	s_cmp_eq_u32 s8, 1
	s_nop 0
	v_writelane_b32 v254, s5, 63
	s_cselect_b64 s[4:5], -1, 0
	v_writelane_b32 v255, s4, 0
	s_cmp_eq_u32 s8, 0
	s_nop 0
	v_writelane_b32 v255, s5, 1
	s_cselect_b64 s[4:5], -1, 0
	v_writelane_b32 v255, s4, 2
	s_nop 1
	v_writelane_b32 v255, s5, 3
	s_lshl_b32 s4, s9, 2
	s_add_u32 s2, s2, s4
	s_addc_u32 s3, s3, 0
	s_add_u32 s4, s2, 0x1400
	s_addc_u32 s5, s3, 0
	v_writelane_b32 v255, s4, 4
	s_add_u32 s2, s2, 0x2400
	s_addc_u32 s3, s3, 0
	v_writelane_b32 v255, s5, 5
	v_writelane_b32 v255, s2, 6
	s_load_dwordx2 s[20:21], s[0:1], 0x80
	s_load_dwordx4 s[8:11], s[0:1], 0x38
	v_writelane_b32 v255, s0, 62
	v_writelane_b32 v255, s1, 63
	v_writelane_b32 v255, s3, 7
	s_add_u32 s2, s12, 0x83400
	s_addc_u32 s3, s13, 0
	v_writelane_b32 v255, s2, 8
	s_movk_i32 s4, 0x81
	s_movk_i32 s5, 0x7fff
	v_writelane_b32 v255, s3, 9
	s_add_u32 s2, s12, 0x83500
	s_addc_u32 s3, s13, 0
	v_writelane_b32 v255, s2, 10
	s_nop 1
	v_writelane_b32 v255, s3, 11
	s_add_i32 s2, 0, 0x26440
	v_writelane_b32 v255, s2, 12
	s_add_i32 s2, 0, 0x26444
	v_writelane_b32 v255, s2, 13
	s_waitcnt lgkmcnt(0)
	v_writelane_b32 v255, s8, 14
	s_mov_b64 s[2:3], -1
	s_nop 0
	v_writelane_b32 v255, s9, 15
	v_writelane_b32 v255, s10, 16
	v_writelane_b32 v255, s11, 17
	v_writelane_b32 v255, s72, 18
	v_writelane_b32 v255, s73, 19
	v_writelane_b32 v255, s78, 20
	s_nop 1
	v_writelane_b32 v255, s79, 21
	v_writelane_b32 v255, s36, 22
	v_writelane_b32 v255, s58, 23
	s_nop 1
	v_writelane_b32 v255, s59, 24
	s_branch .LBB0_205

; __global__ void __launch_bounds__(NTHREADS, 2) mega_fwd(Args args) {
;     ...
;           pg8::Gemm g{P_XB, (const bf16*)(P_WL(l) + OFF_WGU1), S, NGU, D}; pg8::StaticOrder so; so.init(S, NGU, Gp, bidp);
;           pg8::EpiSwiglu E{P_H, FF, P_SSQX + (size_t)(3 * l + 0) * S * 8};
;           pg8::gemm_phase<pg8::EpiSwiglu, pg8::StaticOrder, true, true, D, D, 0>(lds, g, so, E, wavep);
.LBB0_235:
	s_cmpk_lt_i32 s72, 0x80
	s_cbranch_scc1 .Ldc_retA
	v_readlane_b32 s0, v254, 2
	s_nop 1
	s_cmpk_lg_i32 s0, 0x100
	s_cbranch_scc1 .Ldc_retA
	s_mov_b32 s98, 1
	s_branch .Ldc_enter

; #define WS_BASE() unsigned char* ws = args.ws; int bidp = bid, Gp = G, wavep = wave; asm volatile("" : "+s"(ws), "+s"(bidp), "+s"(Gp), "+s"(wavep));
; __global__ void __launch_bounds__(NTHREADS, 2) mega_fwd(Args args) {
;     ...
;         { WS_BASE();
;           pg8::Gemm g{P_XB, (const bf16*)(P_WL(l) + OFF_WGU2), S, NGU, D}; pg8::StaticOrder so; so.init(S, NGU, Gp, bidp);
;           pg8::EpiSwiglu E{P_H, FF, P_SSQX + (size_t)(3 * l + 2) * S * 8};
;           pg8::gemm_phase<pg8::EpiSwiglu, pg8::StaticOrder, true, true, D, D, 0>(lds, g, so, E, wavep); }
.LBB0_786:
	s_cmpk_lt_i32 s72, 0x80
	s_cbranch_scc1 .Ldc_retB
	v_readlane_b32 s0, v254, 2
	s_nop 1
	s_cmpk_lg_i32 s0, 0x100
	s_cbranch_scc1 .Ldc_retB
	s_mov_b32 s98, 2
	s_branch .Ldc_enter

; __global__ void __launch_bounds__(NTHREADS, 2) mega_fwd(Args args) {
	.amdhsa_kernel _Z8mega_fwd4Args
		.amdhsa_group_segment_fixed_size 0
		.amdhsa_private_segment_fixed_size 0
		.amdhsa_kernarg_size 400
		.amdhsa_user_sgpr_count 2
		.amdhsa_user_sgpr_dispatch_ptr 0
		.amdhsa_user_sgpr_queue_ptr 0
		.amdhsa_user_sgpr_kernarg_segment_ptr 1
		.amdhsa_user_sgpr_dispatch_id 0
		.amdhsa_user_sgpr_kernarg_preload_length 0
		.amdhsa_user_sgpr_kernarg_preload_offset 0
		.amdhsa_user_sgpr_private_segment_size 0
		.amdhsa_uses_dynamic_stack 0
		.amdhsa_enable_private_segment 0
		.amdhsa_system_sgpr_workgroup_id_x 1
		.amdhsa_system_sgpr_workgroup_id_y 0
		.amdhsa_system_sgpr_workgroup_id_z 0
		.amdhsa_system_sgpr_workgroup_info 0
		.amdhsa_system_vgpr_workitem_id 2
		.amdhsa_next_free_vgpr 256
		.amdhsa_next_free_sgpr 102
		.amdhsa_accum_offset 256
		.amdhsa_reserve_vcc 1
		.amdhsa_float_round_mode_32 0
		.amdhsa_float_round_mode_16_64 0
		.amdhsa_float_denorm_mode_32 3
		.amdhsa_float_denorm_mode_16_64 3
		.amdhsa_dx10_clamp 1
		.amdhsa_ieee_mode 1
		.amdhsa_fp16_overflow 0
		.amdhsa_tg_split 0
		.amdhsa_exception_fp_ieee_invalid_op 0
		.amdhsa_exception_fp_denorm_src 0
		.amdhsa_exception_fp_ieee_div_zero 0
		.amdhsa_exception_fp_ieee_overflow 0
		.amdhsa_exception_fp_ieee_underflow 0
		.amdhsa_exception_fp_ieee_inexact 0
		.amdhsa_exception_int_div_zero 0
	.end_amdhsa_kernel

; __global__ void __launch_bounds__(NTHREADS, 2) mega_fwd(Args args) {
amdhsa.kernels:
  - .agpr_count:     0
    .args:
      - .offset:         0
        .size:           144
        .value_kind:     by_value
      - .offset:         144
        .size:           4
        .value_kind:     hidden_block_count_x
      - .offset:         148
        .size:           4
        .value_kind:     hidden_block_count_y
      - .offset:         152
        .size:           4
        .value_kind:     hidden_block_count_z
      - .offset:         156
        .size:           2
        .value_kind:     hidden_group_size_x
      - .offset:         158
        .size:           2
        .value_kind:     hidden_group_size_y
      - .offset:         160
        .size:           2
        .value_kind:     hidden_group_size_z
      - .offset:         162
        .size:           2
        .value_kind:     hidden_remainder_x
      - .offset:         164
        .size:           2
        .value_kind:     hidden_remainder_y
      - .offset:         166
        .size:           2
        .value_kind:     hidden_remainder_z
      - .offset:         184
        .size:           8
        .value_kind:     hidden_global_offset_x
      - .offset:         192
        .size:           8
        .value_kind:     hidden_global_offset_y
      - .offset:         200
        .size:           8
        .value_kind:     hidden_global_offset_z
      - .offset:         208
        .size:           2
        .value_kind:     hidden_grid_dims
      - .offset:         232
        .size:           8
        .value_kind:     hidden_multigrid_sync_arg
      - .offset:         264
        .size:           4
        .value_kind:     hidden_dynamic_lds_size
    .group_segment_fixed_size: 0
    .kernarg_segment_align: 8
    .kernarg_segment_size: 400
    .language:       OpenCL C
    .language_version:
      - 2
      - 0
    .max_flat_workgroup_size: 512
    .name:           _Z8mega_fwd4Args
    .private_segment_fixed_size: 0
    .sgpr_count:     108
    .sgpr_spill_count: 95
    .symbol:         _Z8mega_fwd4Args.kd
    .uniform_work_group_size: 1
    .uses_dynamic_stack: false
    .vgpr_count:     256
    .vgpr_spill_count: 0
    .wavefront_size: 64
